# in-projection GEMM K-loop hand-written: SGPR-based LDS-DMA addressing, fragment reads issued ahead, DMA issued right after the barrier
# speedup vs baseline: 1.1089x; 1.0180x over previous
.LBB0_243:
	s_lshl_b64 s[0:1], s[18:19], 18
	s_add_u32 s76, s4, s0
	s_addc_u32 s77, s5, s1
	s_mov_b32 s43, s19
	s_lshl_b64 s[16:17], s[42:43], 18
	s_add_u32 s36, s60, s16
	s_addc_u32 s37, s49, s17
	s_mov_b32 s78, s36
	s_mov_b32 s79, s37
	v_lshrrev_b32_e32 v96, 3, v138
	v_bfe_u32 v97, v138, 4, 3
	v_and_b32_e32 v98, 7, v138
	v_xor_b32_e32 v97, v97, v98
	v_lshlrev_b32_e32 v97, 4, v97
	v_lshl_add_u32 v240, v96, 11, v97
	v_add_u32_e32 v241, 0x10000, v240
	v_add_u32_e32 v242, 0x20000, v240
	v_add_u32_e32 v243, 0x30000, v240
	v_lshrrev_b32_e32 v99, 6, v138
	v_and_b32_e32 v100, 15, v138
	v_readfirstlane_b32 s80, v99
	v_bfe_u32 v101, v138, 4, 2
	v_lshrrev_b32_e32 v102, 1, v100
	v_xor_b32_e32 v102, v102, v101
	v_lshlrev_b32_e32 v102, 4, v102
	s_lshl_b32 s81, s80, 10
	v_lshrrev_b32_e32 v103, 1, v99
	v_and_b32_e32 v99, 1, v99
	v_lshl_add_u32 v96, v103, 6, v100
	v_lshl_add_u32 v244, v96, 7, v102
	v_xor_b32_e32 v245, 64, v244
	v_lshl_add_u32 v96, v99, 6, v100
	v_lshl_add_u32 v246, v96, 7, v102
	v_add_u32_e32 v246, 0x4000, v246
	v_xor_b32_e32 v247, 64, v246
	v_lshlrev_b32_e32 v96, 6, v103
	v_lshl_add_u32 v96, v101, 2, v96
	s_movk_i32 s0, 0x210
	v_mul_lo_u32 v96, v96, s0
	v_lshl_add_u32 v97, v99, 6, v100
	v_lshl_add_u32 v248, v97, 2, v96
	v_mov_b32_e32 v0, 0
	v_mov_b32_e32 v1, 0
	v_mov_b32_e32 v2, 0
	v_mov_b32_e32 v3, 0
	v_mov_b32_e32 v4, 0
	v_mov_b32_e32 v5, 0
	v_mov_b32_e32 v6, 0
	v_mov_b32_e32 v7, 0
	v_mov_b32_e32 v8, 0
	v_mov_b32_e32 v9, 0
	v_mov_b32_e32 v10, 0
	v_mov_b32_e32 v11, 0
	v_mov_b32_e32 v12, 0
	v_mov_b32_e32 v13, 0
	v_mov_b32_e32 v14, 0
	v_mov_b32_e32 v15, 0
	v_mov_b32_e32 v16, 0
	v_mov_b32_e32 v17, 0
	v_mov_b32_e32 v18, 0
	v_mov_b32_e32 v19, 0
	v_mov_b32_e32 v20, 0
	v_mov_b32_e32 v21, 0
	v_mov_b32_e32 v22, 0
	v_mov_b32_e32 v23, 0
	v_mov_b32_e32 v24, 0
	v_mov_b32_e32 v25, 0
	v_mov_b32_e32 v26, 0
	v_mov_b32_e32 v27, 0
	v_mov_b32_e32 v28, 0
	v_mov_b32_e32 v29, 0
	v_mov_b32_e32 v30, 0
	v_mov_b32_e32 v31, 0
	v_mov_b32_e32 v32, 0
	v_mov_b32_e32 v33, 0
	v_mov_b32_e32 v34, 0
	v_mov_b32_e32 v35, 0
	v_mov_b32_e32 v36, 0
	v_mov_b32_e32 v37, 0
	v_mov_b32_e32 v38, 0
	v_mov_b32_e32 v39, 0
	v_mov_b32_e32 v40, 0
	v_mov_b32_e32 v41, 0
	v_mov_b32_e32 v42, 0
	v_mov_b32_e32 v43, 0
	v_mov_b32_e32 v44, 0
	v_mov_b32_e32 v45, 0
	v_mov_b32_e32 v46, 0
	v_mov_b32_e32 v47, 0
	v_mov_b32_e32 v48, 0
	v_mov_b32_e32 v49, 0
	v_mov_b32_e32 v50, 0
	v_mov_b32_e32 v51, 0
	v_mov_b32_e32 v52, 0
	v_mov_b32_e32 v53, 0
	v_mov_b32_e32 v54, 0
	v_mov_b32_e32 v55, 0
	v_mov_b32_e32 v56, 0
	v_mov_b32_e32 v57, 0
	v_mov_b32_e32 v58, 0
	v_mov_b32_e32 v59, 0
	v_mov_b32_e32 v60, 0
	v_mov_b32_e32 v61, 0
	v_mov_b32_e32 v62, 0
	v_mov_b32_e32 v63, 0
	s_barrier
	s_add_i32 m0, s81, 0
	s_nop 0
	global_load_lds_dwordx4 v240, s[76:77]
	s_add_i32 m0, s81, 4096
	s_nop 0
	global_load_lds_dwordx4 v241, s[76:77]
	s_add_i32 m0, s81, 8192
	s_nop 0
	global_load_lds_dwordx4 v242, s[76:77]
	s_add_i32 m0, s81, 12288
	s_nop 0
	global_load_lds_dwordx4 v243, s[76:77]
	s_add_i32 m0, s81, 16384
	s_nop 0
	global_load_lds_dwordx4 v240, s[78:79]
	s_add_i32 m0, s81, 20480
	s_nop 0
	global_load_lds_dwordx4 v241, s[78:79]
	s_add_i32 m0, s81, 24576
	s_nop 0
	global_load_lds_dwordx4 v242, s[78:79]
	s_add_i32 m0, s81, 28672
	s_nop 0
	global_load_lds_dwordx4 v243, s[78:79]
	s_add_u32 s76, s76, 0x80
	s_addc_u32 s77, s77, 0
	s_add_u32 s78, s78, 0x80
	s_addc_u32 s79, s79, 0
	s_movk_i32 s82, 7
.Lip_loop:
	s_waitcnt vmcnt(0)
	s_barrier
	ds_read_b128 v[64:67], v244 offset:0
	ds_read_b128 v[80:83], v246 offset:0
	ds_read_b128 v[84:87], v246 offset:2048
	ds_read_b128 v[88:91], v246 offset:4096
	ds_read_b128 v[92:95], v246 offset:6144
	ds_read_b128 v[68:71], v244 offset:2048
	ds_read_b128 v[72:75], v244 offset:4096
	ds_read_b128 v[76:79], v244 offset:6144
	s_waitcnt lgkmcnt(6)
	v_mfma_f32_16x16x32_bf16 v[0:3], v[64:67], v[80:83], v[0:3]
	ds_read_b128 v[208:211], v245 offset:0
	s_add_i32 m0, s81, 32768
	s_waitcnt lgkmcnt(6)
	v_mfma_f32_16x16x32_bf16 v[4:7], v[64:67], v[84:87], v[4:7]
	ds_read_b128 v[224:227], v247 offset:0
	global_load_lds_dwordx4 v240, s[76:77]
	s_waitcnt lgkmcnt(6)
	v_mfma_f32_16x16x32_bf16 v[8:11], v[64:67], v[88:91], v[8:11]
	ds_read_b128 v[228:231], v247 offset:2048
	s_add_i32 m0, s81, 36864
	s_waitcnt lgkmcnt(6)
	v_mfma_f32_16x16x32_bf16 v[12:15], v[64:67], v[92:95], v[12:15]
	ds_read_b128 v[232:235], v247 offset:4096
	global_load_lds_dwordx4 v241, s[76:77]
	s_waitcnt lgkmcnt(6)
	v_mfma_f32_16x16x32_bf16 v[16:19], v[68:71], v[80:83], v[16:19]
	ds_read_b128 v[236:239], v247 offset:6144
	s_add_i32 m0, s81, 40960
	v_mfma_f32_16x16x32_bf16 v[20:23], v[68:71], v[84:87], v[20:23]
	ds_read_b128 v[212:215], v245 offset:2048
	global_load_lds_dwordx4 v242, s[76:77]
	v_mfma_f32_16x16x32_bf16 v[24:27], v[68:71], v[88:91], v[24:27]
	ds_read_b128 v[216:219], v245 offset:4096
	s_add_i32 m0, s81, 45056
	v_mfma_f32_16x16x32_bf16 v[28:31], v[68:71], v[92:95], v[28:31]
	ds_read_b128 v[220:223], v245 offset:6144
	global_load_lds_dwordx4 v243, s[76:77]
	s_waitcnt lgkmcnt(9)
	v_mfma_f32_16x16x32_bf16 v[32:35], v[72:75], v[80:83], v[32:35]
	s_add_i32 m0, s81, 49152
	v_mfma_f32_16x16x32_bf16 v[36:39], v[72:75], v[84:87], v[36:39]
	global_load_lds_dwordx4 v240, s[78:79]
	v_mfma_f32_16x16x32_bf16 v[40:43], v[72:75], v[88:91], v[40:43]
	s_add_i32 m0, s81, 53248
	v_mfma_f32_16x16x32_bf16 v[44:47], v[72:75], v[92:95], v[44:47]
	global_load_lds_dwordx4 v241, s[78:79]
	s_waitcnt lgkmcnt(8)
	v_mfma_f32_16x16x32_bf16 v[48:51], v[76:79], v[80:83], v[48:51]
	s_add_i32 m0, s81, 57344
	v_mfma_f32_16x16x32_bf16 v[52:55], v[76:79], v[84:87], v[52:55]
	global_load_lds_dwordx4 v242, s[78:79]
	v_mfma_f32_16x16x32_bf16 v[56:59], v[76:79], v[88:91], v[56:59]
	s_add_i32 m0, s81, 61440
	v_mfma_f32_16x16x32_bf16 v[60:63], v[76:79], v[92:95], v[60:63]
	global_load_lds_dwordx4 v243, s[78:79]
	s_waitcnt lgkmcnt(6)
	v_mfma_f32_16x16x32_bf16 v[0:3], v[208:211], v[224:227], v[0:3]
	s_add_u32 s76, s76, 0x80
	s_addc_u32 s77, s77, 0
	s_waitcnt lgkmcnt(5)
	v_mfma_f32_16x16x32_bf16 v[4:7], v[208:211], v[228:231], v[4:7]
	s_waitcnt lgkmcnt(4)
	v_mfma_f32_16x16x32_bf16 v[8:11], v[208:211], v[232:235], v[8:11]
	s_add_u32 s78, s78, 0x80
	s_addc_u32 s79, s79, 0
	s_waitcnt lgkmcnt(3)
	v_mfma_f32_16x16x32_bf16 v[12:15], v[208:211], v[236:239], v[12:15]
	s_waitcnt lgkmcnt(2)
	v_mfma_f32_16x16x32_bf16 v[16:19], v[212:215], v[224:227], v[16:19]
	v_mfma_f32_16x16x32_bf16 v[20:23], v[212:215], v[228:231], v[20:23]
	v_mfma_f32_16x16x32_bf16 v[24:27], v[212:215], v[232:235], v[24:27]
	v_mfma_f32_16x16x32_bf16 v[28:31], v[212:215], v[236:239], v[28:31]
	s_waitcnt lgkmcnt(1)
	v_mfma_f32_16x16x32_bf16 v[32:35], v[216:219], v[224:227], v[32:35]
	v_mfma_f32_16x16x32_bf16 v[36:39], v[216:219], v[228:231], v[36:39]
	v_mfma_f32_16x16x32_bf16 v[40:43], v[216:219], v[232:235], v[40:43]
	v_mfma_f32_16x16x32_bf16 v[44:47], v[216:219], v[236:239], v[44:47]
	s_waitcnt lgkmcnt(0)
	v_mfma_f32_16x16x32_bf16 v[48:51], v[220:223], v[224:227], v[48:51]
	v_mfma_f32_16x16x32_bf16 v[52:55], v[220:223], v[228:231], v[52:55]
	v_mfma_f32_16x16x32_bf16 v[56:59], v[220:223], v[232:235], v[56:59]
	v_mfma_f32_16x16x32_bf16 v[60:63], v[220:223], v[236:239], v[60:63]
	s_waitcnt vmcnt(0)
	s_barrier
	ds_read_b128 v[64:67], v244 offset:32768
	ds_read_b128 v[80:83], v246 offset:32768
	ds_read_b128 v[84:87], v246 offset:34816
	ds_read_b128 v[88:91], v246 offset:36864
	ds_read_b128 v[92:95], v246 offset:38912
	ds_read_b128 v[68:71], v244 offset:34816
	ds_read_b128 v[72:75], v244 offset:36864
	ds_read_b128 v[76:79], v244 offset:38912
	s_waitcnt lgkmcnt(6)
	v_mfma_f32_16x16x32_bf16 v[0:3], v[64:67], v[80:83], v[0:3]
	ds_read_b128 v[208:211], v245 offset:32768
	s_add_i32 m0, s81, 0
	s_waitcnt lgkmcnt(6)
	v_mfma_f32_16x16x32_bf16 v[4:7], v[64:67], v[84:87], v[4:7]
	ds_read_b128 v[224:227], v247 offset:32768
	global_load_lds_dwordx4 v240, s[76:77]
	s_waitcnt lgkmcnt(6)
	v_mfma_f32_16x16x32_bf16 v[8:11], v[64:67], v[88:91], v[8:11]
	ds_read_b128 v[228:231], v247 offset:34816
	s_add_i32 m0, s81, 4096
	s_waitcnt lgkmcnt(6)
	v_mfma_f32_16x16x32_bf16 v[12:15], v[64:67], v[92:95], v[12:15]
	ds_read_b128 v[232:235], v247 offset:36864
	global_load_lds_dwordx4 v241, s[76:77]
	s_waitcnt lgkmcnt(6)
	v_mfma_f32_16x16x32_bf16 v[16:19], v[68:71], v[80:83], v[16:19]
	ds_read_b128 v[236:239], v247 offset:38912
	s_add_i32 m0, s81, 8192
	v_mfma_f32_16x16x32_bf16 v[20:23], v[68:71], v[84:87], v[20:23]
	ds_read_b128 v[212:215], v245 offset:34816
	global_load_lds_dwordx4 v242, s[76:77]
	v_mfma_f32_16x16x32_bf16 v[24:27], v[68:71], v[88:91], v[24:27]
	ds_read_b128 v[216:219], v245 offset:36864
	s_add_i32 m0, s81, 12288
	v_mfma_f32_16x16x32_bf16 v[28:31], v[68:71], v[92:95], v[28:31]
	ds_read_b128 v[220:223], v245 offset:38912
	global_load_lds_dwordx4 v243, s[76:77]
	s_waitcnt lgkmcnt(9)
	v_mfma_f32_16x16x32_bf16 v[32:35], v[72:75], v[80:83], v[32:35]
	s_add_i32 m0, s81, 16384
	v_mfma_f32_16x16x32_bf16 v[36:39], v[72:75], v[84:87], v[36:39]
	global_load_lds_dwordx4 v240, s[78:79]
	v_mfma_f32_16x16x32_bf16 v[40:43], v[72:75], v[88:91], v[40:43]
	s_add_i32 m0, s81, 20480
	v_mfma_f32_16x16x32_bf16 v[44:47], v[72:75], v[92:95], v[44:47]
	global_load_lds_dwordx4 v241, s[78:79]
	s_waitcnt lgkmcnt(8)
	v_mfma_f32_16x16x32_bf16 v[48:51], v[76:79], v[80:83], v[48:51]
	s_add_i32 m0, s81, 24576
	v_mfma_f32_16x16x32_bf16 v[52:55], v[76:79], v[84:87], v[52:55]
	global_load_lds_dwordx4 v242, s[78:79]
	v_mfma_f32_16x16x32_bf16 v[56:59], v[76:79], v[88:91], v[56:59]
	s_add_i32 m0, s81, 28672
	v_mfma_f32_16x16x32_bf16 v[60:63], v[76:79], v[92:95], v[60:63]
	global_load_lds_dwordx4 v243, s[78:79]
	s_waitcnt lgkmcnt(6)
	v_mfma_f32_16x16x32_bf16 v[0:3], v[208:211], v[224:227], v[0:3]
	s_add_u32 s76, s76, 0x80
	s_addc_u32 s77, s77, 0
	s_waitcnt lgkmcnt(5)
	v_mfma_f32_16x16x32_bf16 v[4:7], v[208:211], v[228:231], v[4:7]
	s_waitcnt lgkmcnt(4)
	v_mfma_f32_16x16x32_bf16 v[8:11], v[208:211], v[232:235], v[8:11]
	s_add_u32 s78, s78, 0x80
	s_addc_u32 s79, s79, 0
	s_waitcnt lgkmcnt(3)
	v_mfma_f32_16x16x32_bf16 v[12:15], v[208:211], v[236:239], v[12:15]
	s_waitcnt lgkmcnt(2)
	v_mfma_f32_16x16x32_bf16 v[16:19], v[212:215], v[224:227], v[16:19]
	v_mfma_f32_16x16x32_bf16 v[20:23], v[212:215], v[228:231], v[20:23]
	v_mfma_f32_16x16x32_bf16 v[24:27], v[212:215], v[232:235], v[24:27]
	v_mfma_f32_16x16x32_bf16 v[28:31], v[212:215], v[236:239], v[28:31]
	s_waitcnt lgkmcnt(1)
	v_mfma_f32_16x16x32_bf16 v[32:35], v[216:219], v[224:227], v[32:35]
	v_mfma_f32_16x16x32_bf16 v[36:39], v[216:219], v[228:231], v[36:39]
	v_mfma_f32_16x16x32_bf16 v[40:43], v[216:219], v[232:235], v[40:43]
	v_mfma_f32_16x16x32_bf16 v[44:47], v[216:219], v[236:239], v[44:47]
	s_waitcnt lgkmcnt(0)
	v_mfma_f32_16x16x32_bf16 v[48:51], v[220:223], v[224:227], v[48:51]
	v_mfma_f32_16x16x32_bf16 v[52:55], v[220:223], v[228:231], v[52:55]
	v_mfma_f32_16x16x32_bf16 v[56:59], v[220:223], v[232:235], v[56:59]
	v_mfma_f32_16x16x32_bf16 v[60:63], v[220:223], v[236:239], v[60:63]
	s_sub_u32 s82, s82, 1
	s_cmp_lg_u32 s82, 0
	s_cbranch_scc1 .Lip_loop
	s_waitcnt vmcnt(0)
	s_barrier
	ds_read_b128 v[64:67], v244 offset:0
	ds_read_b128 v[80:83], v246 offset:0
	ds_read_b128 v[84:87], v246 offset:2048
	ds_read_b128 v[88:91], v246 offset:4096
	ds_read_b128 v[92:95], v246 offset:6144
	ds_read_b128 v[68:71], v244 offset:2048
	ds_read_b128 v[72:75], v244 offset:4096
	ds_read_b128 v[76:79], v244 offset:6144
	s_waitcnt lgkmcnt(6)
	v_mfma_f32_16x16x32_bf16 v[0:3], v[64:67], v[80:83], v[0:3]
	ds_read_b128 v[208:211], v245 offset:0
	s_add_i32 m0, s81, 32768
	s_waitcnt lgkmcnt(6)
	v_mfma_f32_16x16x32_bf16 v[4:7], v[64:67], v[84:87], v[4:7]
	ds_read_b128 v[224:227], v247 offset:0
	global_load_lds_dwordx4 v240, s[76:77]
	s_waitcnt lgkmcnt(6)
	v_mfma_f32_16x16x32_bf16 v[8:11], v[64:67], v[88:91], v[8:11]
	ds_read_b128 v[228:231], v247 offset:2048
	s_add_i32 m0, s81, 36864
	s_waitcnt lgkmcnt(6)
	v_mfma_f32_16x16x32_bf16 v[12:15], v[64:67], v[92:95], v[12:15]
	ds_read_b128 v[232:235], v247 offset:4096
	global_load_lds_dwordx4 v241, s[76:77]
	s_waitcnt lgkmcnt(6)
	v_mfma_f32_16x16x32_bf16 v[16:19], v[68:71], v[80:83], v[16:19]
	ds_read_b128 v[236:239], v247 offset:6144
	s_add_i32 m0, s81, 40960
	v_mfma_f32_16x16x32_bf16 v[20:23], v[68:71], v[84:87], v[20:23]
	ds_read_b128 v[212:215], v245 offset:2048
	global_load_lds_dwordx4 v242, s[76:77]
	v_mfma_f32_16x16x32_bf16 v[24:27], v[68:71], v[88:91], v[24:27]
	ds_read_b128 v[216:219], v245 offset:4096
	s_add_i32 m0, s81, 45056
	v_mfma_f32_16x16x32_bf16 v[28:31], v[68:71], v[92:95], v[28:31]
	ds_read_b128 v[220:223], v245 offset:6144
	global_load_lds_dwordx4 v243, s[76:77]
	s_waitcnt lgkmcnt(9)
	v_mfma_f32_16x16x32_bf16 v[32:35], v[72:75], v[80:83], v[32:35]
	s_add_i32 m0, s81, 49152
	v_mfma_f32_16x16x32_bf16 v[36:39], v[72:75], v[84:87], v[36:39]
	global_load_lds_dwordx4 v240, s[78:79]
	v_mfma_f32_16x16x32_bf16 v[40:43], v[72:75], v[88:91], v[40:43]
	s_add_i32 m0, s81, 53248
	v_mfma_f32_16x16x32_bf16 v[44:47], v[72:75], v[92:95], v[44:47]
	global_load_lds_dwordx4 v241, s[78:79]
	s_waitcnt lgkmcnt(8)
	v_mfma_f32_16x16x32_bf16 v[48:51], v[76:79], v[80:83], v[48:51]
	s_add_i32 m0, s81, 57344
	v_mfma_f32_16x16x32_bf16 v[52:55], v[76:79], v[84:87], v[52:55]
	global_load_lds_dwordx4 v242, s[78:79]
	v_mfma_f32_16x16x32_bf16 v[56:59], v[76:79], v[88:91], v[56:59]
	s_add_i32 m0, s81, 61440
	v_mfma_f32_16x16x32_bf16 v[60:63], v[76:79], v[92:95], v[60:63]
	global_load_lds_dwordx4 v243, s[78:79]
	s_waitcnt lgkmcnt(6)
	v_mfma_f32_16x16x32_bf16 v[0:3], v[208:211], v[224:227], v[0:3]
	s_add_u32 s76, s76, 0x80
	s_addc_u32 s77, s77, 0
	s_waitcnt lgkmcnt(5)
	v_mfma_f32_16x16x32_bf16 v[4:7], v[208:211], v[228:231], v[4:7]
	s_waitcnt lgkmcnt(4)
	v_mfma_f32_16x16x32_bf16 v[8:11], v[208:211], v[232:235], v[8:11]
	s_add_u32 s78, s78, 0x80
	s_addc_u32 s79, s79, 0
	s_waitcnt lgkmcnt(3)
	v_mfma_f32_16x16x32_bf16 v[12:15], v[208:211], v[236:239], v[12:15]
	s_waitcnt lgkmcnt(2)
	v_mfma_f32_16x16x32_bf16 v[16:19], v[212:215], v[224:227], v[16:19]
	v_mfma_f32_16x16x32_bf16 v[20:23], v[212:215], v[228:231], v[20:23]
	v_mfma_f32_16x16x32_bf16 v[24:27], v[212:215], v[232:235], v[24:27]
	v_mfma_f32_16x16x32_bf16 v[28:31], v[212:215], v[236:239], v[28:31]
	s_waitcnt lgkmcnt(1)
	v_mfma_f32_16x16x32_bf16 v[32:35], v[216:219], v[224:227], v[32:35]
	v_mfma_f32_16x16x32_bf16 v[36:39], v[216:219], v[228:231], v[36:39]
	v_mfma_f32_16x16x32_bf16 v[40:43], v[216:219], v[232:235], v[40:43]
	v_mfma_f32_16x16x32_bf16 v[44:47], v[216:219], v[236:239], v[44:47]
	s_waitcnt lgkmcnt(0)
	v_mfma_f32_16x16x32_bf16 v[48:51], v[220:223], v[224:227], v[48:51]
	v_mfma_f32_16x16x32_bf16 v[52:55], v[220:223], v[228:231], v[52:55]
	v_mfma_f32_16x16x32_bf16 v[56:59], v[220:223], v[232:235], v[56:59]
	v_mfma_f32_16x16x32_bf16 v[60:63], v[220:223], v[236:239], v[60:63]
	s_waitcnt vmcnt(0)
	s_barrier
	ds_read_b128 v[64:67], v244 offset:32768
	ds_read_b128 v[80:83], v246 offset:32768
	ds_read_b128 v[84:87], v246 offset:34816
	ds_read_b128 v[88:91], v246 offset:36864
	ds_read_b128 v[92:95], v246 offset:38912
	ds_read_b128 v[68:71], v244 offset:34816
	ds_read_b128 v[72:75], v244 offset:36864
	ds_read_b128 v[76:79], v244 offset:38912
	s_waitcnt lgkmcnt(6)
	v_mfma_f32_16x16x32_bf16 v[0:3], v[64:67], v[80:83], v[0:3]
	ds_read_b128 v[208:211], v245 offset:32768
	s_waitcnt lgkmcnt(6)
	v_mfma_f32_16x16x32_bf16 v[4:7], v[64:67], v[84:87], v[4:7]
	ds_read_b128 v[224:227], v247 offset:32768
	s_waitcnt lgkmcnt(6)
	v_mfma_f32_16x16x32_bf16 v[8:11], v[64:67], v[88:91], v[8:11]
	ds_read_b128 v[228:231], v247 offset:34816
	s_waitcnt lgkmcnt(6)
	v_mfma_f32_16x16x32_bf16 v[12:15], v[64:67], v[92:95], v[12:15]
	ds_read_b128 v[232:235], v247 offset:36864
	s_waitcnt lgkmcnt(6)
	v_mfma_f32_16x16x32_bf16 v[16:19], v[68:71], v[80:83], v[16:19]
	ds_read_b128 v[236:239], v247 offset:38912
	v_mfma_f32_16x16x32_bf16 v[20:23], v[68:71], v[84:87], v[20:23]
	ds_read_b128 v[212:215], v245 offset:34816
	v_mfma_f32_16x16x32_bf16 v[24:27], v[68:71], v[88:91], v[24:27]
	ds_read_b128 v[216:219], v245 offset:36864
	v_mfma_f32_16x16x32_bf16 v[28:31], v[68:71], v[92:95], v[28:31]
	ds_read_b128 v[220:223], v245 offset:38912
	s_waitcnt lgkmcnt(9)
	v_mfma_f32_16x16x32_bf16 v[32:35], v[72:75], v[80:83], v[32:35]
	v_mfma_f32_16x16x32_bf16 v[36:39], v[72:75], v[84:87], v[36:39]
	v_mfma_f32_16x16x32_bf16 v[40:43], v[72:75], v[88:91], v[40:43]
	v_mfma_f32_16x16x32_bf16 v[44:47], v[72:75], v[92:95], v[44:47]
	s_waitcnt lgkmcnt(8)
	v_mfma_f32_16x16x32_bf16 v[48:51], v[76:79], v[80:83], v[48:51]
	v_mfma_f32_16x16x32_bf16 v[52:55], v[76:79], v[84:87], v[52:55]
	v_mfma_f32_16x16x32_bf16 v[56:59], v[76:79], v[88:91], v[56:59]
	v_mfma_f32_16x16x32_bf16 v[60:63], v[76:79], v[92:95], v[60:63]
	s_waitcnt lgkmcnt(6)
	v_mfma_f32_16x16x32_bf16 v[0:3], v[208:211], v[224:227], v[0:3]
	s_waitcnt lgkmcnt(5)
	v_mfma_f32_16x16x32_bf16 v[4:7], v[208:211], v[228:231], v[4:7]
	s_waitcnt lgkmcnt(4)
	v_mfma_f32_16x16x32_bf16 v[8:11], v[208:211], v[232:235], v[8:11]
	s_waitcnt lgkmcnt(3)
	v_mfma_f32_16x16x32_bf16 v[12:15], v[208:211], v[236:239], v[12:15]
	s_waitcnt lgkmcnt(2)
	v_mfma_f32_16x16x32_bf16 v[16:19], v[212:215], v[224:227], v[16:19]
	v_mfma_f32_16x16x32_bf16 v[20:23], v[212:215], v[228:231], v[20:23]
	v_mfma_f32_16x16x32_bf16 v[24:27], v[212:215], v[232:235], v[24:27]
	v_mfma_f32_16x16x32_bf16 v[28:31], v[212:215], v[236:239], v[28:31]
	s_waitcnt lgkmcnt(1)
	v_mfma_f32_16x16x32_bf16 v[32:35], v[216:219], v[224:227], v[32:35]
	v_mfma_f32_16x16x32_bf16 v[36:39], v[216:219], v[228:231], v[36:39]
	v_mfma_f32_16x16x32_bf16 v[40:43], v[216:219], v[232:235], v[40:43]
	v_mfma_f32_16x16x32_bf16 v[44:47], v[216:219], v[236:239], v[44:47]
	s_waitcnt lgkmcnt(0)
	v_mfma_f32_16x16x32_bf16 v[48:51], v[220:223], v[224:227], v[48:51]
	v_mfma_f32_16x16x32_bf16 v[52:55], v[220:223], v[228:231], v[52:55]
	v_mfma_f32_16x16x32_bf16 v[56:59], v[220:223], v[232:235], v[56:59]
	v_mfma_f32_16x16x32_bf16 v[60:63], v[220:223], v[236:239], v[60:63]
	s_barrier
	ds_write_b32 v248, v0 offset:0
	ds_write_b32 v248, v1 offset:528
	ds_write_b32 v248, v2 offset:1056
	ds_write_b32 v248, v3 offset:1584
	ds_write_b32 v248, v4 offset:64
	ds_write_b32 v248, v5 offset:592
	ds_write_b32 v248, v6 offset:1120
	ds_write_b32 v248, v7 offset:1648
	ds_write_b32 v248, v8 offset:128
	ds_write_b32 v248, v9 offset:656
	ds_write_b32 v248, v10 offset:1184
	ds_write_b32 v248, v11 offset:1712
	ds_write_b32 v248, v12 offset:192
	ds_write_b32 v248, v13 offset:720
	ds_write_b32 v248, v14 offset:1248
	ds_write_b32 v248, v15 offset:1776
	ds_write_b32 v248, v16 offset:8448
	ds_write_b32 v248, v17 offset:8976
	ds_write_b32 v248, v18 offset:9504
	ds_write_b32 v248, v19 offset:10032
	ds_write_b32 v248, v20 offset:8512
	ds_write_b32 v248, v21 offset:9040
	ds_write_b32 v248, v22 offset:9568
	ds_write_b32 v248, v23 offset:10096
	ds_write_b32 v248, v24 offset:8576
	ds_write_b32 v248, v25 offset:9104
	ds_write_b32 v248, v26 offset:9632
	ds_write_b32 v248, v27 offset:10160
	ds_write_b32 v248, v28 offset:8640
	ds_write_b32 v248, v29 offset:9168
	ds_write_b32 v248, v30 offset:9696
	ds_write_b32 v248, v31 offset:10224
	ds_write_b32 v248, v32 offset:16896
	ds_write_b32 v248, v33 offset:17424
	ds_write_b32 v248, v34 offset:17952
	ds_write_b32 v248, v35 offset:18480
	ds_write_b32 v248, v36 offset:16960
	ds_write_b32 v248, v37 offset:17488
	ds_write_b32 v248, v38 offset:18016
	ds_write_b32 v248, v39 offset:18544
	ds_write_b32 v248, v40 offset:17024
	ds_write_b32 v248, v41 offset:17552
	ds_write_b32 v248, v42 offset:18080
	ds_write_b32 v248, v43 offset:18608
	ds_write_b32 v248, v44 offset:17088
	ds_write_b32 v248, v45 offset:17616
	ds_write_b32 v248, v46 offset:18144
	ds_write_b32 v248, v47 offset:18672
	ds_write_b32 v248, v48 offset:25344
	ds_write_b32 v248, v49 offset:25872
	ds_write_b32 v248, v50 offset:26400
	ds_write_b32 v248, v51 offset:26928
	ds_write_b32 v248, v52 offset:25408
	ds_write_b32 v248, v53 offset:25936
	ds_write_b32 v248, v54 offset:26464
	ds_write_b32 v248, v55 offset:26992
	ds_write_b32 v248, v56 offset:25472
	ds_write_b32 v248, v57 offset:26000
	ds_write_b32 v248, v58 offset:26528
	ds_write_b32 v248, v59 offset:27056
	ds_write_b32 v248, v60 offset:25536
	ds_write_b32 v248, v61 offset:26064
	ds_write_b32 v248, v62 offset:26592
	ds_write_b32 v248, v63 offset:27120
	v_mov_b32_e32 v26, v138
	s_lshl_b32 s57, s18, 7
	s_cmpk_lt_u32 s18, 0x80
	s_cselect_b64 s[16:17], -1, 0
	s_mov_b64 s[0:1], -1
	s_mov_b32 s2, 0x40000
	s_cmp_gt_u32 s42, 2
	s_waitcnt lgkmcnt(0)
	s_barrier
	s_cbranch_scc0 .LBB0_270
	s_cmp_lg_u32 s42, 3
	s_cbranch_scc0 .LBB0_272
	s_add_i32 s0, s42, -10
	s_cmp_gt_u32 s0, 7
	s_mov_b64 s[0:1], -1
	s_cbranch_scc0 .LBB0_251
	s_lshl_b32 s0, s42, 7
	s_cmp_lt_u32 s42, 10
	s_movk_i32 s1, 0xfe00
	s_cselect_b32 s1, s1, 0xfffffc00
	s_add_i32 s0, s1, s0
	s_mov_b32 s1, s19
	v_lshlrev_b32_e32 v0, 3, v26
	s_lshl_b64 s[0:1], s[0:1], 1
	v_readlane_b32 s2, v206, 43
	v_and_b32_e32 v1, 0x78, v0
	v_readlane_b32 s3, v206, 44
	s_add_u32 s0, s2, s0
	s_addc_u32 s1, s3, s1
	v_lshlrev_b32_e32 v134, 1, v1
	v_lshlrev_b32_e32 v0, 2, v1
	v_lshl_add_u64 v[2:3], s[0:1], 0, v[134:135]
	s_mov_b32 s0, 0
